# attn3b + DPP min/max with wait states before lane reads + P0 gain hoists + all-16-loads transposes
# speedup vs baseline: 1.0130x; 1.0130x over previous
; #define LDS_WAIT() asm volatile("s_waitcnt lgkmcnt(0)" ::: "memory")
; __device__ __forceinline__ int lane_id() { int l; asm volatile("v_mbcnt_lo_u32_b32 %0, -1, 0\n\tv_mbcnt_hi_u32_b32 %0, -1, %0\n\ts_nop 1" : "=v"(l)); return l; }
; __device__ __forceinline__ unsigned f2ord(float f) { const unsigned u = __float_as_uint(f); return u ^ ((u >> 31) ? 0xFFFFFFFFu : 0x80000000u); }
; __device__ __forceinline__ int topk_compact(LAS u32x2* buf, int cnt, float& tau) {
;     const int lane = lane_id();
;     LDS_WAIT();
;     unsigned key[12], idx[12];
;     unsigned kmin = 0xFFFFFFFFu, kmax = 0u;
; #pragma unroll
;     for (int j = 0; j < 12; ++j) { const int e = j * 64 + lane; const u32x2 v = buf[e]; const bool ok = e < cnt; const unsigned k = f2ord(__uint_as_float(v.x)); key[j] = ok ? k : 0u; idx[j] = v.y;
;         kmin = (ok && k < kmin) ? k : kmin; kmax = (ok && k > kmax) ? k : kmax; }
; #pragma unroll
;     for (int o = 1; o < 64; o <<= 1) { const unsigned a = (unsigned)__shfl_xor((int)kmin, o), b = (unsigned)__shfl_xor((int)kmax, o); kmin = a < kmin ? a : kmin; kmax = b > kmax ? b : kmax; }
;     const unsigned diff = (unsigned)__builtin_amdgcn_readfirstlane((int)(kmin ^ kmax));
;     int bit = diff ? (31 - __builtin_clz(diff)) : -1;
;     unsigned T = (bit >= 0) ? (unsigned)__builtin_amdgcn_readfirstlane((int)kmin) & ~((2u << bit) - 1u) : (unsigned)__builtin_amdgcn_readfirstlane((int)kmin);
.Lidx_compact:
	s_cmpk_lt_i32 s74, 0x101
	s_cbranch_scc1 .LBB0_485
	v_mbcnt_lo_u32_b32 v25, -1, 0
	v_mbcnt_hi_u32_b32 v25, -1, v25
	s_nop 1
	s_waitcnt lgkmcnt(0)
	s_nop 0
	v_lshl_add_u32 v0, v25, 3, s97
	ds_read2st64_b64 v[20:23], v0 offset1:1
	ds_read2st64_b64 v[8:11], v0 offset0:2 offset1:3
	v_add_u32_e32 v2, 64, v25
	v_cmp_gt_i32_e64 s[12:13], s74, v2
	ds_read2st64_b64 v[16:19], v0 offset0:4 offset1:5
	ds_read2st64_b64 v[12:15], v0 offset0:6 offset1:7
	s_waitcnt lgkmcnt(3)
	v_cmp_lt_i32_e32 vcc, -1, v20
	v_add_u32_e32 v27, 0x200, v25
	v_cmp_gt_i32_e64 s[26:27], s74, v27
	v_cndmask_b32_e32 v1, -1, v123, vcc
	v_xor_b32_e32 v1, v1, v20
	v_cmp_gt_i32_e32 vcc, s74, v25
	s_nop 1
	v_cndmask_b32_e32 v24, 0, v1, vcc
	v_cndmask_b32_e32 v1, -1, v1, vcc
	v_cmp_lt_i32_e32 vcc, -1, v22
	s_nop 1
	v_cndmask_b32_e32 v3, -1, v123, vcc
	v_xor_b32_e32 v20, v3, v22
	s_waitcnt lgkmcnt(2)
	v_cmp_lt_i32_e32 vcc, -1, v8
	v_min_u32_e32 v3, v20, v1
	v_cndmask_b32_e64 v1, v1, v3, s[12:13]
	v_cndmask_b32_e32 v4, -1, v123, vcc
	v_max_u32_e32 v2, v20, v24
	v_add_u32_e32 v3, 0x80, v25
	v_xor_b32_e32 v8, v4, v8
	v_cndmask_b32_e64 v2, v24, v2, s[12:13]
	v_min_u32_e32 v4, v8, v1
	v_cmp_gt_i32_e64 s[14:15], s74, v3
	v_cmp_lt_i32_e32 vcc, -1, v10
	v_max_u32_e32 v3, v8, v2
	v_cndmask_b32_e64 v1, v1, v4, s[14:15]
	v_cndmask_b32_e32 v4, -1, v123, vcc
	v_cndmask_b32_e64 v2, v2, v3, s[14:15]
	v_add_u32_e32 v3, 0xc0, v25
	v_xor_b32_e32 v10, v4, v10
	v_min_u32_e32 v4, v10, v1
	v_cmp_gt_i32_e64 s[16:17], s74, v3
	s_waitcnt lgkmcnt(1)
	v_cmp_lt_i32_e32 vcc, -1, v16
	v_max_u32_e32 v3, v10, v2
	v_cndmask_b32_e64 v1, v1, v4, s[16:17]
	v_cndmask_b32_e32 v4, -1, v123, vcc
	v_cndmask_b32_e64 v2, v2, v3, s[16:17]
	v_add_u32_e32 v3, 0x100, v25
	v_xor_b32_e32 v16, v4, v16
	v_min_u32_e32 v4, v16, v1
	v_cmp_gt_i32_e64 s[18:19], s74, v3
	v_cmp_lt_i32_e32 vcc, -1, v18
	v_max_u32_e32 v3, v16, v2
	v_cndmask_b32_e64 v1, v1, v4, s[18:19]
	v_cndmask_b32_e32 v4, -1, v123, vcc
	v_cndmask_b32_e64 v2, v2, v3, s[18:19]
	v_add_u32_e32 v3, 0x140, v25
	v_xor_b32_e32 v18, v4, v18
	v_min_u32_e32 v4, v18, v1
	v_cmp_gt_i32_e64 s[20:21], s74, v3
	s_waitcnt lgkmcnt(0)
	v_cmp_lt_i32_e32 vcc, -1, v12
	v_max_u32_e32 v3, v18, v2
	v_cndmask_b32_e64 v1, v1, v4, s[20:21]
	v_cndmask_b32_e32 v4, -1, v123, vcc
	v_cndmask_b32_e64 v2, v2, v3, s[20:21]
	v_add_u32_e32 v3, 0x180, v25
	v_xor_b32_e32 v12, v4, v12
	v_min_u32_e32 v4, v12, v1
	v_cmp_gt_i32_e64 s[22:23], s74, v3
	v_cmp_lt_i32_e32 vcc, -1, v14
	v_max_u32_e32 v3, v12, v2
	v_cndmask_b32_e64 v1, v1, v4, s[22:23]
	v_cndmask_b32_e32 v4, -1, v123, vcc
	v_cndmask_b32_e64 v2, v2, v3, s[22:23]
	v_add_u32_e32 v3, 0x1c0, v25
	v_xor_b32_e32 v14, v4, v14
	v_min_u32_e32 v4, v14, v1
	v_cmp_gt_i32_e64 s[24:25], s74, v3
	s_nop 1
	v_cndmask_b32_e64 v22, v1, v4, s[24:25]
	ds_read2st64_b64 v[4:7], v0 offset0:8 offset1:9
	v_max_u32_e32 v1, v14, v2
	v_cndmask_b32_e64 v26, v2, v1, s[24:25]
	ds_read2st64_b64 v[0:3], v0 offset0:10 offset1:11
	s_waitcnt lgkmcnt(1)
	v_cmp_lt_i32_e32 vcc, -1, v4
	s_nop 1
	v_cndmask_b32_e32 v28, -1, v123, vcc
	v_xor_b32_e32 v4, v28, v4
	v_min_u32_e32 v28, v4, v22
	v_cmp_lt_i32_e32 vcc, -1, v6
	v_cndmask_b32_e64 v22, v22, v28, s[26:27]
	v_max_u32_e32 v27, v4, v26
	v_cndmask_b32_e32 v28, -1, v123, vcc
	v_cndmask_b32_e64 v26, v26, v27, s[26:27]
	v_add_u32_e32 v27, 0x240, v25
	v_xor_b32_e32 v6, v28, v6
	v_min_u32_e32 v28, v6, v22
	v_cmp_gt_i32_e64 s[28:29], s74, v27
	s_waitcnt lgkmcnt(0)
	v_cmp_lt_i32_e32 vcc, -1, v0
	v_max_u32_e32 v27, v6, v26
	v_cndmask_b32_e64 v22, v22, v28, s[28:29]
	v_cndmask_b32_e32 v28, -1, v123, vcc
	v_cndmask_b32_e64 v26, v26, v27, s[28:29]
	v_add_u32_e32 v27, 0x280, v25
	v_xor_b32_e32 v0, v28, v0
	v_cmp_gt_i32_e64 s[30:31], s74, v27
	v_max_u32_e32 v27, v0, v26
	v_cmp_lt_i32_e32 vcc, -1, v2
	v_cndmask_b32_e64 v26, v26, v27, s[30:31]
	v_min_u32_e32 v28, v0, v22
	v_cndmask_b32_e32 v27, -1, v123, vcc
	v_add_u32_e32 v25, 0x2c0, v25
	v_xor_b32_e32 v2, v27, v2
	v_cndmask_b32_e64 v22, v22, v28, s[30:31]
	v_cmp_gt_i32_e64 s[34:35], s74, v25
	v_max_u32_e32 v25, v2, v26
	v_min_u32_e32 v27, v2, v22
	v_cndmask_b32_e64 v25, v26, v25, s[34:35]
	v_and_b32_e32 v26, 64, v144
	v_cndmask_b32_e64 v22, v22, v27, s[34:35]
	v_add_u32_e32 v26, 64, v26
	s_nop 1
	v_min_u32_dpp v22, v22, v22 row_shr:1 row_mask:0xf bank_mask:0xf
	v_max_u32_dpp v25, v25, v25 row_shr:1 row_mask:0xf bank_mask:0xf
	s_nop 0
	v_min_u32_dpp v22, v22, v22 row_shr:2 row_mask:0xf bank_mask:0xf
	v_max_u32_dpp v25, v25, v25 row_shr:2 row_mask:0xf bank_mask:0xf
	s_nop 0
	v_min_u32_dpp v22, v22, v22 row_shr:4 row_mask:0xf bank_mask:0xf
	v_max_u32_dpp v25, v25, v25 row_shr:4 row_mask:0xf bank_mask:0xf
	s_nop 0
	v_min_u32_dpp v22, v22, v22 row_shr:8 row_mask:0xf bank_mask:0xf
	v_max_u32_dpp v25, v25, v25 row_shr:8 row_mask:0xf bank_mask:0xf
	s_nop 0
	s_nop 1
	v_readlane_b32 s4, v22, 15
	v_readlane_b32 s5, v22, 31
	s_min_u32 s4, s4, s5
	v_readlane_b32 s5, v22, 47
	s_min_u32 s4, s4, s5
	v_readlane_b32 s5, v22, 63
	s_min_u32 s4, s4, s5
	v_mov_b32_e32 v22, s4
	v_readlane_b32 s4, v25, 15
	v_readlane_b32 s5, v25, 31
	s_max_u32 s4, s4, s5
	v_readlane_b32 s5, v25, 47
	s_max_u32 s4, s4, s5
	v_readlane_b32 s5, v25, 63
	s_max_u32 s4, s4, s5
	v_mov_b32_e32 v25, s4
	v_xor_b32_e32 v25, v22, v25
	s_nop 0
	v_readfirstlane_b32 s5, v25
	s_cmp_lg_u32 s5, 0
	s_flbit_i32_b32 s4, s5
	s_cselect_b64 s[36:37], -1, 0
	s_xor_b32 s4, s4, 31
	s_cmp_eq_u32 s5, 0
	s_cbranch_scc1 .LBB0_456
	v_readfirstlane_b32 s5, v22
	s_lshl_b32 s94, -2, s4
	s_and_b32 s5, s5, s94
	s_cbranch_execnz .LBB0_395

; #define LDS_WAIT() asm volatile("s_waitcnt lgkmcnt(0)" ::: "memory")
; __device__ __forceinline__ int lane_id() { int l; asm volatile("v_mbcnt_lo_u32_b32 %0, -1, 0\n\tv_mbcnt_hi_u32_b32 %0, -1, %0\n\ts_nop 1" : "=v"(l)); return l; }
; __device__ __forceinline__ unsigned f2ord(float f) { const unsigned u = __float_as_uint(f); return u ^ ((u >> 31) ? 0xFFFFFFFFu : 0x80000000u); }
; __device__ __forceinline__ int topk_compact(LAS u32x2* buf, int cnt, float& tau) {
;     const int lane = lane_id();
;     LDS_WAIT();
;     unsigned key[12], idx[12];
;     unsigned kmin = 0xFFFFFFFFu, kmax = 0u;
; #pragma unroll
;     for (int j = 0; j < 12; ++j) { const int e = j * 64 + lane; const u32x2 v = buf[e]; const bool ok = e < cnt; const unsigned k = f2ord(__uint_as_float(v.x)); key[j] = ok ? k : 0u; idx[j] = v.y;
;         kmin = (ok && k < kmin) ? k : kmin; kmax = (ok && k > kmax) ? k : kmax; }
; #pragma unroll
;     for (int o = 1; o < 64; o <<= 1) { const unsigned a = (unsigned)__shfl_xor((int)kmin, o), b = (unsigned)__shfl_xor((int)kmax, o); kmin = a < kmin ? a : kmin; kmax = b > kmax ? b : kmax; }
;     const unsigned diff = (unsigned)__builtin_amdgcn_readfirstlane((int)(kmin ^ kmax));
;     int bit = diff ? (31 - __builtin_clz(diff)) : -1;
;     unsigned T = (bit >= 0) ? (unsigned)__builtin_amdgcn_readfirstlane((int)kmin) & ~((2u << bit) - 1u) : (unsigned)__builtin_amdgcn_readfirstlane((int)kmin);
.LBB0_485:
	s_cmpk_lt_i32 s75, 0x101
	s_cbranch_scc1 .LBB0_571
	v_mbcnt_lo_u32_b32 v25, -1, 0
	v_mbcnt_hi_u32_b32 v25, -1, v25
	s_nop 1
	s_waitcnt lgkmcnt(0)
	s_nop 0
	v_lshl_add_u32 v0, v25, 3, s97
	ds_read2st64_b64 v[20:23], v0 offset0:12 offset1:13
	ds_read2st64_b64 v[8:11], v0 offset0:14 offset1:15
	v_add_u32_e32 v2, 64, v25
	v_cmp_gt_i32_e64 s[12:13], s75, v2
	ds_read2st64_b64 v[16:19], v0 offset0:16 offset1:17
	ds_read2st64_b64 v[12:15], v0 offset0:18 offset1:19
	s_waitcnt lgkmcnt(3)
	v_cmp_lt_i32_e32 vcc, -1, v20
	v_add_u32_e32 v27, 0x200, v25
	v_cmp_gt_i32_e64 s[26:27], s75, v27
	v_cndmask_b32_e32 v1, -1, v123, vcc
	v_xor_b32_e32 v1, v1, v20
	v_cmp_gt_i32_e32 vcc, s75, v25
	s_nop 1
	v_cndmask_b32_e32 v24, 0, v1, vcc
	v_cndmask_b32_e32 v1, -1, v1, vcc
	v_cmp_lt_i32_e32 vcc, -1, v22
	s_nop 1
	v_cndmask_b32_e32 v3, -1, v123, vcc
	v_xor_b32_e32 v20, v3, v22
	s_waitcnt lgkmcnt(2)
	v_cmp_lt_i32_e32 vcc, -1, v8
	v_min_u32_e32 v3, v20, v1
	v_cndmask_b32_e64 v1, v1, v3, s[12:13]
	v_cndmask_b32_e32 v4, -1, v123, vcc
	v_max_u32_e32 v2, v20, v24
	v_add_u32_e32 v3, 0x80, v25
	v_xor_b32_e32 v8, v4, v8
	v_cndmask_b32_e64 v2, v24, v2, s[12:13]
	v_min_u32_e32 v4, v8, v1
	v_cmp_gt_i32_e64 s[14:15], s75, v3
	v_cmp_lt_i32_e32 vcc, -1, v10
	v_max_u32_e32 v3, v8, v2
	v_cndmask_b32_e64 v1, v1, v4, s[14:15]
	v_cndmask_b32_e32 v4, -1, v123, vcc
	v_cndmask_b32_e64 v2, v2, v3, s[14:15]
	v_add_u32_e32 v3, 0xc0, v25
	v_xor_b32_e32 v10, v4, v10
	v_min_u32_e32 v4, v10, v1
	v_cmp_gt_i32_e64 s[16:17], s75, v3
	s_waitcnt lgkmcnt(1)
	v_cmp_lt_i32_e32 vcc, -1, v16
	v_max_u32_e32 v3, v10, v2
	v_cndmask_b32_e64 v1, v1, v4, s[16:17]
	v_cndmask_b32_e32 v4, -1, v123, vcc
	v_cndmask_b32_e64 v2, v2, v3, s[16:17]
	v_add_u32_e32 v3, 0x100, v25
	v_xor_b32_e32 v16, v4, v16
	v_min_u32_e32 v4, v16, v1
	v_cmp_gt_i32_e64 s[18:19], s75, v3
	v_cmp_lt_i32_e32 vcc, -1, v18
	v_max_u32_e32 v3, v16, v2
	v_cndmask_b32_e64 v1, v1, v4, s[18:19]
	v_cndmask_b32_e32 v4, -1, v123, vcc
	v_cndmask_b32_e64 v2, v2, v3, s[18:19]
	v_add_u32_e32 v3, 0x140, v25
	v_xor_b32_e32 v18, v4, v18
	v_min_u32_e32 v4, v18, v1
	v_cmp_gt_i32_e64 s[20:21], s75, v3
	s_waitcnt lgkmcnt(0)
	v_cmp_lt_i32_e32 vcc, -1, v12
	v_max_u32_e32 v3, v18, v2
	v_cndmask_b32_e64 v1, v1, v4, s[20:21]
	v_cndmask_b32_e32 v4, -1, v123, vcc
	v_cndmask_b32_e64 v2, v2, v3, s[20:21]
	v_add_u32_e32 v3, 0x180, v25
	v_xor_b32_e32 v12, v4, v12
	v_min_u32_e32 v4, v12, v1
	v_cmp_gt_i32_e64 s[22:23], s75, v3
	v_cmp_lt_i32_e32 vcc, -1, v14
	v_max_u32_e32 v3, v12, v2
	v_cndmask_b32_e64 v1, v1, v4, s[22:23]
	v_cndmask_b32_e32 v4, -1, v123, vcc
	v_cndmask_b32_e64 v2, v2, v3, s[22:23]
	v_add_u32_e32 v3, 0x1c0, v25
	v_xor_b32_e32 v14, v4, v14
	v_min_u32_e32 v4, v14, v1
	v_cmp_gt_i32_e64 s[24:25], s75, v3
	s_nop 1
	v_cndmask_b32_e64 v22, v1, v4, s[24:25]
	ds_read2st64_b64 v[4:7], v0 offset0:20 offset1:21
	v_max_u32_e32 v1, v14, v2
	v_cndmask_b32_e64 v26, v2, v1, s[24:25]
	ds_read2st64_b64 v[0:3], v0 offset0:22 offset1:23
	s_waitcnt lgkmcnt(1)
	v_cmp_lt_i32_e32 vcc, -1, v4
	s_nop 1
	v_cndmask_b32_e32 v28, -1, v123, vcc
	v_xor_b32_e32 v4, v28, v4
	v_min_u32_e32 v28, v4, v22
	v_cmp_lt_i32_e32 vcc, -1, v6
	v_cndmask_b32_e64 v22, v22, v28, s[26:27]
	v_max_u32_e32 v27, v4, v26
	v_cndmask_b32_e32 v28, -1, v123, vcc
	v_cndmask_b32_e64 v26, v26, v27, s[26:27]
	v_add_u32_e32 v27, 0x240, v25
	v_xor_b32_e32 v6, v28, v6
	v_min_u32_e32 v28, v6, v22
	v_cmp_gt_i32_e64 s[28:29], s75, v27
	s_waitcnt lgkmcnt(0)
	v_cmp_lt_i32_e32 vcc, -1, v0
	v_max_u32_e32 v27, v6, v26
	v_cndmask_b32_e64 v22, v22, v28, s[28:29]
	v_cndmask_b32_e32 v28, -1, v123, vcc
	v_cndmask_b32_e64 v26, v26, v27, s[28:29]
	v_add_u32_e32 v27, 0x280, v25
	v_xor_b32_e32 v0, v28, v0
	v_cmp_gt_i32_e64 s[30:31], s75, v27
	v_max_u32_e32 v27, v0, v26
	v_cmp_lt_i32_e32 vcc, -1, v2
	v_cndmask_b32_e64 v26, v26, v27, s[30:31]
	v_min_u32_e32 v28, v0, v22
	v_cndmask_b32_e32 v27, -1, v123, vcc
	v_add_u32_e32 v25, 0x2c0, v25
	v_xor_b32_e32 v2, v27, v2
	v_cndmask_b32_e64 v22, v22, v28, s[30:31]
	v_cmp_gt_i32_e64 s[34:35], s75, v25
	v_max_u32_e32 v25, v2, v26
	v_min_u32_e32 v27, v2, v22
	v_cndmask_b32_e64 v25, v26, v25, s[34:35]
	v_and_b32_e32 v26, 64, v144
	v_cndmask_b32_e64 v22, v22, v27, s[34:35]
	v_add_u32_e32 v26, 64, v26
	s_nop 1
	v_min_u32_dpp v22, v22, v22 row_shr:1 row_mask:0xf bank_mask:0xf
	v_max_u32_dpp v25, v25, v25 row_shr:1 row_mask:0xf bank_mask:0xf
	s_nop 0
	v_min_u32_dpp v22, v22, v22 row_shr:2 row_mask:0xf bank_mask:0xf
	v_max_u32_dpp v25, v25, v25 row_shr:2 row_mask:0xf bank_mask:0xf
	s_nop 0
	v_min_u32_dpp v22, v22, v22 row_shr:4 row_mask:0xf bank_mask:0xf
	v_max_u32_dpp v25, v25, v25 row_shr:4 row_mask:0xf bank_mask:0xf
	s_nop 0
	v_min_u32_dpp v22, v22, v22 row_shr:8 row_mask:0xf bank_mask:0xf
	v_max_u32_dpp v25, v25, v25 row_shr:8 row_mask:0xf bank_mask:0xf
	s_nop 0
	s_nop 1
	v_readlane_b32 s4, v22, 15
	v_readlane_b32 s5, v22, 31
	s_min_u32 s4, s4, s5
	v_readlane_b32 s5, v22, 47
	s_min_u32 s4, s4, s5
	v_readlane_b32 s5, v22, 63
	s_min_u32 s4, s4, s5
	v_mov_b32_e32 v22, s4
	v_readlane_b32 s4, v25, 15
	v_readlane_b32 s5, v25, 31
	s_max_u32 s4, s4, s5
	v_readlane_b32 s5, v25, 47
	s_max_u32 s4, s4, s5
	v_readlane_b32 s5, v25, 63
	s_max_u32 s4, s4, s5
	v_mov_b32_e32 v25, s4
	v_xor_b32_e32 v25, v22, v25
	s_nop 0
	v_readfirstlane_b32 s5, v25
	s_cmp_lg_u32 s5, 0
	s_flbit_i32_b32 s4, s5
	s_cselect_b64 s[36:37], -1, 0
	s_xor_b32 s4, s4, 31
	s_cmp_eq_u32 s5, 0
	s_cbranch_scc1 .LBB0_542
	v_readfirstlane_b32 s5, v22
	s_lshl_b32 s94, -2, s4
	s_and_b32 s5, s5, s94
	s_cbranch_execnz .LBB0_489

; #define LDS_WAIT() asm volatile("s_waitcnt lgkmcnt(0)" ::: "memory")
; __device__ __forceinline__ int lane_id() { int l; asm volatile("v_mbcnt_lo_u32_b32 %0, -1, 0\n\tv_mbcnt_hi_u32_b32 %0, -1, %0\n\ts_nop 1" : "=v"(l)); return l; }
; __device__ __forceinline__ unsigned f2ord(float f) { const unsigned u = __float_as_uint(f); return u ^ ((u >> 31) ? 0xFFFFFFFFu : 0x80000000u); }
; __device__ __forceinline__ int topk_compact(LAS u32x2* buf, int cnt, float& tau) {
;     const int lane = lane_id();
;     LDS_WAIT();
;     unsigned key[12], idx[12];
;     unsigned kmin = 0xFFFFFFFFu, kmax = 0u;
; #pragma unroll
;     for (int j = 0; j < 12; ++j) { const int e = j * 64 + lane; const u32x2 v = buf[e]; const bool ok = e < cnt; const unsigned k = f2ord(__uint_as_float(v.x)); key[j] = ok ? k : 0u; idx[j] = v.y;
;         kmin = (ok && k < kmin) ? k : kmin; kmax = (ok && k > kmax) ? k : kmax; }
; #pragma unroll
;     for (int o = 1; o < 64; o <<= 1) { const unsigned a = (unsigned)__shfl_xor((int)kmin, o), b = (unsigned)__shfl_xor((int)kmax, o); kmin = a < kmin ? a : kmin; kmax = b > kmax ? b : kmax; }
;     const unsigned diff = (unsigned)__builtin_amdgcn_readfirstlane((int)(kmin ^ kmax));
;     int bit = diff ? (31 - __builtin_clz(diff)) : -1;
;     unsigned T = (bit >= 0) ? (unsigned)__builtin_amdgcn_readfirstlane((int)kmin) & ~((2u << bit) - 1u) : (unsigned)__builtin_amdgcn_readfirstlane((int)kmin);
.LBB0_573:
	s_cmpk_gt_i32 s74, 0x100
	s_cbranch_scc0 .LBB0_659
	v_mbcnt_lo_u32_b32 v25, -1, 0
	v_mbcnt_hi_u32_b32 v25, -1, v25
	s_nop 1
	s_waitcnt lgkmcnt(0)
	s_waitcnt vmcnt(0)
	v_lshl_add_u32 v0, v25, 3, s97
	ds_read2st64_b64 v[20:23], v0 offset1:1
	ds_read2st64_b64 v[8:11], v0 offset0:2 offset1:3
	v_add_u32_e32 v2, 64, v25
	v_cmp_gt_i32_e64 s[6:7], s74, v2
	ds_read2st64_b64 v[16:19], v0 offset0:4 offset1:5
	ds_read2st64_b64 v[12:15], v0 offset0:6 offset1:7
	s_waitcnt lgkmcnt(3)
	v_cmp_lt_i32_e32 vcc, -1, v20
	v_add_u32_e32 v27, 0x200, v25
	v_cmp_gt_i32_e64 s[20:21], s74, v27
	v_cndmask_b32_e32 v1, -1, v123, vcc
	v_xor_b32_e32 v1, v1, v20
	v_cmp_gt_i32_e32 vcc, s74, v25
	s_nop 1
	v_cndmask_b32_e32 v24, 0, v1, vcc
	v_cndmask_b32_e32 v1, -1, v1, vcc
	v_cmp_lt_i32_e32 vcc, -1, v22
	s_nop 1
	v_cndmask_b32_e32 v3, -1, v123, vcc
	v_xor_b32_e32 v20, v3, v22
	s_waitcnt lgkmcnt(2)
	v_cmp_lt_i32_e32 vcc, -1, v8
	v_min_u32_e32 v3, v20, v1
	v_cndmask_b32_e64 v1, v1, v3, s[6:7]
	v_cndmask_b32_e32 v4, -1, v123, vcc
	v_max_u32_e32 v2, v20, v24
	v_add_u32_e32 v3, 0x80, v25
	v_xor_b32_e32 v8, v4, v8
	v_cndmask_b32_e64 v2, v24, v2, s[6:7]
	v_min_u32_e32 v4, v8, v1
	v_cmp_gt_i32_e64 s[8:9], s74, v3
	v_cmp_lt_i32_e32 vcc, -1, v10
	v_max_u32_e32 v3, v8, v2
	v_cndmask_b32_e64 v1, v1, v4, s[8:9]
	v_cndmask_b32_e32 v4, -1, v123, vcc
	v_cndmask_b32_e64 v2, v2, v3, s[8:9]
	v_add_u32_e32 v3, 0xc0, v25
	v_xor_b32_e32 v10, v4, v10
	v_min_u32_e32 v4, v10, v1
	v_cmp_gt_i32_e64 s[10:11], s74, v3
	s_waitcnt lgkmcnt(1)
	v_cmp_lt_i32_e32 vcc, -1, v16
	v_max_u32_e32 v3, v10, v2
	v_cndmask_b32_e64 v1, v1, v4, s[10:11]
	v_cndmask_b32_e32 v4, -1, v123, vcc
	v_cndmask_b32_e64 v2, v2, v3, s[10:11]
	v_add_u32_e32 v3, 0x100, v25
	v_xor_b32_e32 v16, v4, v16
	v_min_u32_e32 v4, v16, v1
	v_cmp_gt_i32_e64 s[12:13], s74, v3
	v_cmp_lt_i32_e32 vcc, -1, v18
	v_max_u32_e32 v3, v16, v2
	v_cndmask_b32_e64 v1, v1, v4, s[12:13]
	v_cndmask_b32_e32 v4, -1, v123, vcc
	v_cndmask_b32_e64 v2, v2, v3, s[12:13]
	v_add_u32_e32 v3, 0x140, v25
	v_xor_b32_e32 v18, v4, v18
	v_min_u32_e32 v4, v18, v1
	v_cmp_gt_i32_e64 s[14:15], s74, v3
	s_waitcnt lgkmcnt(0)
	v_cmp_lt_i32_e32 vcc, -1, v12
	v_max_u32_e32 v3, v18, v2
	v_cndmask_b32_e64 v1, v1, v4, s[14:15]
	v_cndmask_b32_e32 v4, -1, v123, vcc
	v_cndmask_b32_e64 v2, v2, v3, s[14:15]
	v_add_u32_e32 v3, 0x180, v25
	v_xor_b32_e32 v12, v4, v12
	v_min_u32_e32 v4, v12, v1
	v_cmp_gt_i32_e64 s[16:17], s74, v3
	v_cmp_lt_i32_e32 vcc, -1, v14
	v_max_u32_e32 v3, v12, v2
	v_cndmask_b32_e64 v1, v1, v4, s[16:17]
	v_cndmask_b32_e32 v4, -1, v123, vcc
	v_cndmask_b32_e64 v2, v2, v3, s[16:17]
	v_add_u32_e32 v3, 0x1c0, v25
	v_xor_b32_e32 v14, v4, v14
	v_min_u32_e32 v4, v14, v1
	v_cmp_gt_i32_e64 s[18:19], s74, v3
	s_nop 1
	v_cndmask_b32_e64 v22, v1, v4, s[18:19]
	ds_read2st64_b64 v[4:7], v0 offset0:8 offset1:9
	v_max_u32_e32 v1, v14, v2
	v_cndmask_b32_e64 v26, v2, v1, s[18:19]
	ds_read2st64_b64 v[0:3], v0 offset0:10 offset1:11
	s_waitcnt lgkmcnt(1)
	v_cmp_lt_i32_e32 vcc, -1, v4
	s_nop 1
	v_cndmask_b32_e32 v28, -1, v123, vcc
	v_xor_b32_e32 v4, v28, v4
	v_min_u32_e32 v28, v4, v22
	v_cmp_lt_i32_e32 vcc, -1, v6
	v_cndmask_b32_e64 v22, v22, v28, s[20:21]
	v_max_u32_e32 v27, v4, v26
	v_cndmask_b32_e32 v28, -1, v123, vcc
	v_cndmask_b32_e64 v26, v26, v27, s[20:21]
	v_add_u32_e32 v27, 0x240, v25
	v_xor_b32_e32 v6, v28, v6
	v_min_u32_e32 v28, v6, v22
	v_cmp_gt_i32_e64 s[22:23], s74, v27
	s_waitcnt lgkmcnt(0)
	v_cmp_lt_i32_e32 vcc, -1, v0
	v_max_u32_e32 v27, v6, v26
	v_cndmask_b32_e64 v22, v22, v28, s[22:23]
	v_cndmask_b32_e32 v28, -1, v123, vcc
	v_cndmask_b32_e64 v26, v26, v27, s[22:23]
	v_add_u32_e32 v27, 0x280, v25
	v_xor_b32_e32 v0, v28, v0
	v_cmp_gt_i32_e64 s[24:25], s74, v27
	v_max_u32_e32 v27, v0, v26
	v_cmp_lt_i32_e32 vcc, -1, v2
	v_cndmask_b32_e64 v26, v26, v27, s[24:25]
	v_min_u32_e32 v28, v0, v22
	v_cndmask_b32_e32 v27, -1, v123, vcc
	v_add_u32_e32 v25, 0x2c0, v25
	v_xor_b32_e32 v2, v27, v2
	v_cndmask_b32_e64 v22, v22, v28, s[24:25]
	v_cmp_gt_i32_e64 s[26:27], s74, v25
	v_max_u32_e32 v25, v2, v26
	v_min_u32_e32 v27, v2, v22
	v_cndmask_b32_e64 v25, v26, v25, s[26:27]
	v_and_b32_e32 v26, 64, v144
	v_cndmask_b32_e64 v22, v22, v27, s[26:27]
	v_add_u32_e32 v26, 64, v26
	s_nop 1
	v_min_u32_dpp v22, v22, v22 row_shr:1 row_mask:0xf bank_mask:0xf
	v_max_u32_dpp v25, v25, v25 row_shr:1 row_mask:0xf bank_mask:0xf
	s_nop 0
	v_min_u32_dpp v22, v22, v22 row_shr:2 row_mask:0xf bank_mask:0xf
	v_max_u32_dpp v25, v25, v25 row_shr:2 row_mask:0xf bank_mask:0xf
	s_nop 0
	v_min_u32_dpp v22, v22, v22 row_shr:4 row_mask:0xf bank_mask:0xf
	v_max_u32_dpp v25, v25, v25 row_shr:4 row_mask:0xf bank_mask:0xf
	s_nop 0
	v_min_u32_dpp v22, v22, v22 row_shr:8 row_mask:0xf bank_mask:0xf
	v_max_u32_dpp v25, v25, v25 row_shr:8 row_mask:0xf bank_mask:0xf
	s_nop 0
	s_nop 1
	v_readlane_b32 s4, v22, 15
	v_readlane_b32 s5, v22, 31
	s_min_u32 s4, s4, s5
	v_readlane_b32 s5, v22, 47
	s_min_u32 s4, s4, s5
	v_readlane_b32 s5, v22, 63
	s_min_u32 s4, s4, s5
	v_mov_b32_e32 v22, s4
	v_readlane_b32 s4, v25, 15
	v_readlane_b32 s5, v25, 31
	s_max_u32 s4, s4, s5
	v_readlane_b32 s5, v25, 47
	s_max_u32 s4, s4, s5
	v_readlane_b32 s5, v25, 63
	s_max_u32 s4, s4, s5
	v_mov_b32_e32 v25, s4
	v_xor_b32_e32 v25, v22, v25
	s_nop 0
	v_readfirstlane_b32 s5, v25
	s_cmp_lg_u32 s5, 0
	s_flbit_i32_b32 s4, s5
	s_cselect_b64 s[28:29], -1, 0
	s_xor_b32 s4, s4, 31
	s_cmp_eq_u32 s5, 0
	s_cbranch_scc1 .LBB0_630
	v_readfirstlane_b32 s5, v22
	s_lshl_b32 s30, -2, s4
	s_and_b32 s5, s5, s30
	s_cbranch_execnz .LBB0_577

; #define LDS_WAIT() asm volatile("s_waitcnt lgkmcnt(0)" ::: "memory")
; __device__ __forceinline__ int lane_id() { int l; asm volatile("v_mbcnt_lo_u32_b32 %0, -1, 0\n\tv_mbcnt_hi_u32_b32 %0, -1, %0\n\ts_nop 1" : "=v"(l)); return l; }
; __device__ __forceinline__ unsigned f2ord(float f) { const unsigned u = __float_as_uint(f); return u ^ ((u >> 31) ? 0xFFFFFFFFu : 0x80000000u); }
; __device__ __forceinline__ int topk_compact(LAS u32x2* buf, int cnt, float& tau) {
;     const int lane = lane_id();
;     LDS_WAIT();
;     unsigned key[12], idx[12];
;     unsigned kmin = 0xFFFFFFFFu, kmax = 0u;
; #pragma unroll
;     for (int j = 0; j < 12; ++j) { const int e = j * 64 + lane; const u32x2 v = buf[e]; const bool ok = e < cnt; const unsigned k = f2ord(__uint_as_float(v.x)); key[j] = ok ? k : 0u; idx[j] = v.y;
;         kmin = (ok && k < kmin) ? k : kmin; kmax = (ok && k > kmax) ? k : kmax; }
; #pragma unroll
;     for (int o = 1; o < 64; o <<= 1) { const unsigned a = (unsigned)__shfl_xor((int)kmin, o), b = (unsigned)__shfl_xor((int)kmax, o); kmin = a < kmin ? a : kmin; kmax = b > kmax ? b : kmax; }
;     const unsigned diff = (unsigned)__builtin_amdgcn_readfirstlane((int)(kmin ^ kmax));
;     int bit = diff ? (31 - __builtin_clz(diff)) : -1;
;     unsigned T = (bit >= 0) ? (unsigned)__builtin_amdgcn_readfirstlane((int)kmin) & ~((2u << bit) - 1u) : (unsigned)__builtin_amdgcn_readfirstlane((int)kmin);
.LBB0_659:
	s_cmpk_lt_i32 s75, 0x101
	s_cbranch_scc1 .LBB0_745
	v_mbcnt_lo_u32_b32 v25, -1, 0
	v_mbcnt_hi_u32_b32 v25, -1, v25
	s_nop 1
	s_waitcnt lgkmcnt(0)
	s_waitcnt vmcnt(0)
	v_lshl_add_u32 v0, v25, 3, s97
	ds_read2st64_b64 v[20:23], v0 offset0:12 offset1:13
	ds_read2st64_b64 v[8:11], v0 offset0:14 offset1:15
	v_add_u32_e32 v2, 64, v25
	v_cmp_gt_i32_e64 s[6:7], s75, v2
	ds_read2st64_b64 v[16:19], v0 offset0:16 offset1:17
	ds_read2st64_b64 v[12:15], v0 offset0:18 offset1:19
	s_waitcnt lgkmcnt(3)
	v_cmp_lt_i32_e32 vcc, -1, v20
	v_add_u32_e32 v27, 0x200, v25
	v_cmp_gt_i32_e64 s[20:21], s75, v27
	v_cndmask_b32_e32 v1, -1, v123, vcc
	v_xor_b32_e32 v1, v1, v20
	v_cmp_gt_i32_e32 vcc, s75, v25
	s_nop 1
	v_cndmask_b32_e32 v24, 0, v1, vcc
	v_cndmask_b32_e32 v1, -1, v1, vcc
	v_cmp_lt_i32_e32 vcc, -1, v22
	s_nop 1
	v_cndmask_b32_e32 v3, -1, v123, vcc
	v_xor_b32_e32 v20, v3, v22
	s_waitcnt lgkmcnt(2)
	v_cmp_lt_i32_e32 vcc, -1, v8
	v_min_u32_e32 v3, v20, v1
	v_cndmask_b32_e64 v1, v1, v3, s[6:7]
	v_cndmask_b32_e32 v4, -1, v123, vcc
	v_max_u32_e32 v2, v20, v24
	v_add_u32_e32 v3, 0x80, v25
	v_xor_b32_e32 v8, v4, v8
	v_cndmask_b32_e64 v2, v24, v2, s[6:7]
	v_min_u32_e32 v4, v8, v1
	v_cmp_gt_i32_e64 s[8:9], s75, v3
	v_cmp_lt_i32_e32 vcc, -1, v10
	v_max_u32_e32 v3, v8, v2
	v_cndmask_b32_e64 v1, v1, v4, s[8:9]
	v_cndmask_b32_e32 v4, -1, v123, vcc
	v_cndmask_b32_e64 v2, v2, v3, s[8:9]
	v_add_u32_e32 v3, 0xc0, v25
	v_xor_b32_e32 v10, v4, v10
	v_min_u32_e32 v4, v10, v1
	v_cmp_gt_i32_e64 s[10:11], s75, v3
	s_waitcnt lgkmcnt(1)
	v_cmp_lt_i32_e32 vcc, -1, v16
	v_max_u32_e32 v3, v10, v2
	v_cndmask_b32_e64 v1, v1, v4, s[10:11]
	v_cndmask_b32_e32 v4, -1, v123, vcc
	v_cndmask_b32_e64 v2, v2, v3, s[10:11]
	v_add_u32_e32 v3, 0x100, v25
	v_xor_b32_e32 v16, v4, v16
	v_min_u32_e32 v4, v16, v1
	v_cmp_gt_i32_e64 s[12:13], s75, v3
	v_cmp_lt_i32_e32 vcc, -1, v18
	v_max_u32_e32 v3, v16, v2
	v_cndmask_b32_e64 v1, v1, v4, s[12:13]
	v_cndmask_b32_e32 v4, -1, v123, vcc
	v_cndmask_b32_e64 v2, v2, v3, s[12:13]
	v_add_u32_e32 v3, 0x140, v25
	v_xor_b32_e32 v18, v4, v18
	v_min_u32_e32 v4, v18, v1
	v_cmp_gt_i32_e64 s[14:15], s75, v3
	s_waitcnt lgkmcnt(0)
	v_cmp_lt_i32_e32 vcc, -1, v12
	v_max_u32_e32 v3, v18, v2
	v_cndmask_b32_e64 v1, v1, v4, s[14:15]
	v_cndmask_b32_e32 v4, -1, v123, vcc
	v_cndmask_b32_e64 v2, v2, v3, s[14:15]
	v_add_u32_e32 v3, 0x180, v25
	v_xor_b32_e32 v12, v4, v12
	v_min_u32_e32 v4, v12, v1
	v_cmp_gt_i32_e64 s[16:17], s75, v3
	v_cmp_lt_i32_e32 vcc, -1, v14
	v_max_u32_e32 v3, v12, v2
	v_cndmask_b32_e64 v1, v1, v4, s[16:17]
	v_cndmask_b32_e32 v4, -1, v123, vcc
	v_cndmask_b32_e64 v2, v2, v3, s[16:17]
	v_add_u32_e32 v3, 0x1c0, v25
	v_xor_b32_e32 v14, v4, v14
	v_min_u32_e32 v4, v14, v1
	v_cmp_gt_i32_e64 s[18:19], s75, v3
	s_nop 1
	v_cndmask_b32_e64 v22, v1, v4, s[18:19]
	ds_read2st64_b64 v[4:7], v0 offset0:20 offset1:21
	v_max_u32_e32 v1, v14, v2
	v_cndmask_b32_e64 v26, v2, v1, s[18:19]
	ds_read2st64_b64 v[0:3], v0 offset0:22 offset1:23
	s_waitcnt lgkmcnt(1)
	v_cmp_lt_i32_e32 vcc, -1, v4
	s_nop 1
	v_cndmask_b32_e32 v28, -1, v123, vcc
	v_xor_b32_e32 v4, v28, v4
	v_min_u32_e32 v28, v4, v22
	v_cmp_lt_i32_e32 vcc, -1, v6
	v_cndmask_b32_e64 v22, v22, v28, s[20:21]
	v_max_u32_e32 v27, v4, v26
	v_cndmask_b32_e32 v28, -1, v123, vcc
	v_cndmask_b32_e64 v26, v26, v27, s[20:21]
	v_add_u32_e32 v27, 0x240, v25
	v_xor_b32_e32 v6, v28, v6
	v_min_u32_e32 v28, v6, v22
	v_cmp_gt_i32_e64 s[22:23], s75, v27
	s_waitcnt lgkmcnt(0)
	v_cmp_lt_i32_e32 vcc, -1, v0
	v_max_u32_e32 v27, v6, v26
	v_cndmask_b32_e64 v22, v22, v28, s[22:23]
	v_cndmask_b32_e32 v28, -1, v123, vcc
	v_cndmask_b32_e64 v26, v26, v27, s[22:23]
	v_add_u32_e32 v27, 0x280, v25
	v_xor_b32_e32 v0, v28, v0
	v_cmp_gt_i32_e64 s[24:25], s75, v27
	v_max_u32_e32 v27, v0, v26
	v_cmp_lt_i32_e32 vcc, -1, v2
	v_cndmask_b32_e64 v26, v26, v27, s[24:25]
	v_min_u32_e32 v28, v0, v22
	v_cndmask_b32_e32 v27, -1, v123, vcc
	v_add_u32_e32 v25, 0x2c0, v25
	v_xor_b32_e32 v2, v27, v2
	v_cndmask_b32_e64 v22, v22, v28, s[24:25]
	v_cmp_gt_i32_e64 s[26:27], s75, v25
	v_max_u32_e32 v25, v2, v26
	v_min_u32_e32 v27, v2, v22
	v_cndmask_b32_e64 v25, v26, v25, s[26:27]
	v_and_b32_e32 v26, 64, v144
	v_cndmask_b32_e64 v22, v22, v27, s[26:27]
	v_add_u32_e32 v26, 64, v26
	s_nop 1
	v_min_u32_dpp v22, v22, v22 row_shr:1 row_mask:0xf bank_mask:0xf
	v_max_u32_dpp v25, v25, v25 row_shr:1 row_mask:0xf bank_mask:0xf
	s_nop 0
	v_min_u32_dpp v22, v22, v22 row_shr:2 row_mask:0xf bank_mask:0xf
	v_max_u32_dpp v25, v25, v25 row_shr:2 row_mask:0xf bank_mask:0xf
	s_nop 0
	v_min_u32_dpp v22, v22, v22 row_shr:4 row_mask:0xf bank_mask:0xf
	v_max_u32_dpp v25, v25, v25 row_shr:4 row_mask:0xf bank_mask:0xf
	s_nop 0
	v_min_u32_dpp v22, v22, v22 row_shr:8 row_mask:0xf bank_mask:0xf
	v_max_u32_dpp v25, v25, v25 row_shr:8 row_mask:0xf bank_mask:0xf
	s_nop 0
	s_nop 1
	v_readlane_b32 s4, v22, 15
	v_readlane_b32 s5, v22, 31
	s_min_u32 s4, s4, s5
	v_readlane_b32 s5, v22, 47
	s_min_u32 s4, s4, s5
	v_readlane_b32 s5, v22, 63
	s_min_u32 s4, s4, s5
	v_mov_b32_e32 v22, s4
	v_readlane_b32 s4, v25, 15
	v_readlane_b32 s5, v25, 31
	s_max_u32 s4, s4, s5
	v_readlane_b32 s5, v25, 47
	s_max_u32 s4, s4, s5
	v_readlane_b32 s5, v25, 63
	s_max_u32 s4, s4, s5
	v_mov_b32_e32 v25, s4
	v_xor_b32_e32 v25, v22, v25
	s_nop 0
	v_readfirstlane_b32 s5, v25
	s_cmp_lg_u32 s5, 0
	s_flbit_i32_b32 s4, s5
	s_cselect_b64 s[28:29], -1, 0
	s_xor_b32 s4, s4, 31
	s_cmp_eq_u32 s5, 0
	s_cbranch_scc1 .LBB0_716
	v_readfirstlane_b32 s5, v22
	s_lshl_b32 s30, -2, s4
	s_and_b32 s5, s5, s30
	s_cbranch_execnz .LBB0_663
